# attention: waves whose 32 query rows lie past the padded sequence skip all tile compute; the 32 two-tile units go to CUs 224-255
# speedup vs baseline: 1.0014x; 1.0014x over previous
; __device__ __forceinline__ void attn_phase(LAS unsigned char* lds, bf16_t* p5, const bf16_t* vt, const float* relb, const float* dalam, const float* subln, float lam_init, int ocol) {
;     ...
;     for (int r = 0;; ++r) {
;         const int idx = (r & 1) ? r * G + (G - 1 - c) : r * G + c;
;         if (r * G >= 33 * 32) break;
;         if (idx >= 33 * 32) continue;
;         const int qt = 32 - idx / 32, bh = idx & 31, b = bh >> 3, h = bh & 7;
;         const int njt = (2 * qt + 2) < 65 ? (2 * qt + 2) : 65;
;         const int qrow0 = qt * 128 + rgi * 32;
;         __syncthreads();
;         if (tid < 128) { const int d = tid; int bk = d; if (d >= 16) { bk = 16 + (int)(logf((float)d * (1.0f / 16.0f)) * (16.0f / logf(8.0f))); if (bk > 31) bk = 31; } btab[d] = relb[bk * 8 + h] * LOG2E; }
.LBB0_643:
	s_mul_i32 s19, s41, s64
	s_cmpk_gt_i32 s19, 0x41f
	s_mov_b32 s30, 5
	s_cbranch_scc1 .LBB0_790
	s_and_b32 s30, s41, 5
	s_cmp_eq_u32 s30, 0
	v_readlane_b32 s24, v253, 18
	s_cselect_b32 s24, s2, s24
	s_add_i32 s19, s24, s19
	s_cmpk_gt_i32 s19, 0x41f
	s_mov_b32 s30, 7
	s_cbranch_scc1 .LBB0_790
	s_and_b32 s30, s19, 7
	s_barrier
	s_and_saveexec_b64 s[24:25], s[42:43]
	s_cbranch_execz .LBB0_647
	v_or_b32_e32 v2, s30, v179
	v_ashrrev_i32_e32 v3, 31, v2
	v_lshl_add_u64 v[2:3], v[2:3], 2, s[0:1]
	global_load_dword v0, v[2:3], off
	s_waitcnt vmcnt(0)
	v_mul_f32_e32 v0, 0x3fb8aa3b, v0
	ds_write_b32 v143, v0

; #define ATT_LOAD(j) do { _Pragma("unroll") for (int i = 0; i < 2; ++i) { const int id = tid + 512 * i; \
;             kreg[i] = *(const u32x4*)(kbase + (size_t)((j) * 64 + (id >> 4)) * LDP + (id & 15) * 8); \
;             vreg[i] = *(const u32x4*)(vbase + (size_t)(id >> 3) * TP + (j) * 64 + (id & 7) * 8); } } while (0)
; #define ATT_STORE(buf) do { _Pragma("unroll") for (int i = 0; i < 2; ++i) { const int id = tid + 512 * i; \
;             *(LAS u32x4*)(lds + (buf) * KBYTES + (id >> 4) * KPITCH + (id & 15) * 16) = kreg[i]; \
;             *(LAS u32x4*)(lds + 2 * KBYTES + (buf) * VBYTES + (id >> 3) * VPITCH + (id & 7) * 16) = vreg[i]; } } while (0)
; __device__ __forceinline__ void attn_phase(LAS unsigned char* lds, bf16_t* p5, const bf16_t* vt, const float* relb, const float* dalam, const float* subln, float lam_init, int ocol) {
;     ...
;         const int njt = (2 * qt + 2) < 65 ? (2 * qt + 2) : 65;
;         const int qrow0 = qt * 128 + rgi * 32;
;         __syncthreads();
;         if (tid < 128) { const int d = tid; int bk = d; if (d >= 16) { bk = 16 + (int)(logf((float)d * (1.0f / 16.0f)) * (16.0f / logf(8.0f))); if (bk > 31) bk = 31; } btab[d] = relb[bk * 8 + h] * LOG2E; }
;         const float bfar = relb[31 * 8 + h] * LOG2E;
;         bf16x8 qf[2][2];
; #pragma unroll
;         for (int rg = 0; rg < 2; ++rg) { const int q = qrow0 + 16 * rg + lq, qc = q < TP ? q : TP - 1;
; #pragma unroll
;             for (int s = 0; s < 2; ++s) qf[rg][s] = *(const bf16x8*)(p5 + ((size_t)b * TP + qc) * LDP + C_Q + h * 128 + cc * 64 + s * 32 + 8 * g4); }
;         f32x4 O[2][8]; float mrow[2], lrow[2];
; #pragma unroll
;         for (int rg = 0; rg < 2; ++rg) { mrow[rg] = -INFINITY; lrow[rg] = 0.f;
; #pragma unroll
;             for (int k = 0; k < 8; ++k) O[rg][k] = (f32x4){0.f, 0.f, 0.f, 0.f}; }
;         u32x4 kreg[2], vreg[2];
;         const bf16_t* kbase = p5 + (size_t)b * TP * LDP + C_K + h * 128; const bf16_t* vbase = vt + (size_t)bh * 128 * TP;
;     ...
;         ATT_LOAD(0); ATT_STORE(0); __syncthreads();
;         for (int j = 0; j < njt; ++j) {
;             if (j + 1 < njt) ATT_LOAD(j + 1);
;             if (j * 64 <= qrow0 + 31) {
.LBB0_666:
	s_lshl_b32 s29, s31, 1
	s_sub_i32 s28, 0, s34
	s_lshl_b32 s19, s30, 7
	s_or_b32 s47, s46, 31
	s_cmpk_lt_i32 s46, 0x1040
	s_cselect_b32 s47, s47, -1
	s_add_i32 s29, s29, 2
	s_cmp_gt_u32 s28, 0xffffffdf
	s_mov_b32 s30, 1
	s_cselect_b32 s48, s29, 0x41
	v_lshl_add_u32 v169, s28, 9, v193
	v_lshl_add_u32 v198, s28, 7, v194
	s_movk_i32 s49, 0xf0
	s_waitcnt vmcnt(3)
	ds_write_b128 v100, v[20:23] offset:17408
	s_waitcnt vmcnt(1)
	ds_write_b128 v101, v[24:27] offset:53248
	ds_write_b128 v102, v[28:31] offset:17408
	s_waitcnt vmcnt(0)
	ds_write_b128 v103, v[32:35] offset:53248
	s_waitcnt lgkmcnt(0)
	s_barrier
